# XCD leader issues its cross-XCD arrival atomic before its L2 invalidate (both still retired by the same wait), all 8 grid barriers
# speedup vs baseline: 1.0081x; 1.0077x over previous
; __device__ __forceinline__ unsigned xb_ld(unsigned* p)              { return __hip_atomic_load(p, __ATOMIC_RELAXED, __HIP_MEMORY_SCOPE_AGENT); }
; __device__ __forceinline__ unsigned xb_add(unsigned* p, unsigned v) { return __hip_atomic_fetch_add(p, v, __ATOMIC_RELAXED, __HIP_MEMORY_SCOPE_AGENT); }
; #define XB_SPIN(cond, bar) do { unsigned _sp = 0; while (cond) { __builtin_amdgcn_s_sleep(1); \
;     if ((++_sp & 255u) == 0u) { if (xb_ld(&(bar)[XB_TMO])) break; if (_sp > XB_SPIN_CAP) { atomicAdd(&(bar)[XB_TMO], 1u); break; } } } } while (0)
; __device__ __forceinline__ void xcd_barrier(const XcdBarrier& b) {
;     ...
;         const unsigned old = xb_add(&bar[XB_XSUB(b.x)], 1u);
;         const unsigned gen = old / nloc;
;         if (old + 1u == (gen + 1u) * nloc) {
;             __builtin_amdgcn_fence(__ATOMIC_RELEASE, "agent");
;             asm volatile("s_waitcnt vmcnt(0)" ::: "memory");
;             const unsigned og = xb_add(&bar[XB_TOP], 1u);
;             const unsigned tg = og / nx;
;             if (og + 1u == (tg + 1u) * nx) xb_add(&bar[XB_TOPGEN], 1u);
;             else XB_SPIN(xb_ld(&bar[XB_TOPGEN]) == tg, bar);
.LBB0_292:
	s_andn2_saveexec_b64 s[0:1], s[0:1]
	s_cbranch_execz .LBB0_308
	v_mov_b32_e32 v1, s34
	v_add_co_u32_e32 v2, vcc, 0x3000, v1
	v_mov_b32_e32 v1, s35
	buffer_wbl2 sc1
	s_waitcnt vmcnt(0)
	v_addc_co_u32_e32 v3, vcc, 0, v1, vcc
	v_mov_b32_e32 v1, 1
	flat_atomic_add v1, v[2:3], v1 offset:1024 sc0
	buffer_inv sc1
	v_cvt_f32_u32_e32 v2, v0
	v_sub_u32_e32 v3, 0, v0
	s_mov_b64 s[6:7], -1
	v_rcp_iflag_f32_e32 v2, v2
	s_nop 0
	v_mul_f32_e32 v2, 0x4f7ffffe, v2
	v_cvt_u32_f32_e32 v2, v2
	v_mul_lo_u32 v3, v3, v2
	v_mul_hi_u32 v3, v2, v3
	v_add_u32_e32 v2, v2, v3
	s_waitcnt vmcnt(0) lgkmcnt(0)
	v_mul_hi_u32 v2, v1, v2
	v_mul_lo_u32 v3, v2, v0
	v_sub_u32_e32 v3, v1, v3
	v_cmp_ge_u32_e32 vcc, v3, v0
	v_add_u32_e32 v4, 1, v2
	s_nop 0
	v_cndmask_b32_e32 v2, v2, v4, vcc
	v_sub_u32_e32 v4, v3, v0
	v_cndmask_b32_e32 v3, v3, v4, vcc
	v_cmp_ge_u32_e32 vcc, v3, v0
	v_add_u32_e32 v3, 1, v2
	s_nop 0
	v_cndmask_b32_e32 v2, v2, v3, vcc
	v_add_u32_e32 v3, 1, v1
	v_mad_u64_u32 v[0:1], s[0:1], v0, v2, v[0:1]
	s_add_u32 s0, s34, 0x3500
	s_addc_u32 s1, s35, 0
	v_cmp_ne_u32_e32 vcc, v3, v0
	v_mov_b64_e32 v[0:1], s[0:1]
	s_and_saveexec_b64 s[4:5], vcc
	s_cbranch_execz .LBB0_305
	v_mov_b64_e32 v[0:1], s[0:1]
	flat_load_dword v0, v[0:1] sc1
	s_mov_b64 s[10:11], 0
	s_waitcnt vmcnt(0) lgkmcnt(0)
	v_cmp_eq_u32_e32 vcc, v0, v2
	s_and_saveexec_b64 s[8:9], vcc
	s_cbranch_execz .LBB0_304
	s_add_u32 s6, s34, 0x200
	s_addc_u32 s7, s35, 0
	s_mov_b32 s23, 1
	s_branch .LBB0_297

; __device__ __forceinline__ unsigned xb_ld(unsigned* p)              { return __hip_atomic_load(p, __ATOMIC_RELAXED, __HIP_MEMORY_SCOPE_AGENT); }
; __device__ __forceinline__ unsigned xb_add(unsigned* p, unsigned v) { return __hip_atomic_fetch_add(p, v, __ATOMIC_RELAXED, __HIP_MEMORY_SCOPE_AGENT); }
; #define XB_SPIN(cond, bar) do { unsigned _sp = 0; while (cond) { __builtin_amdgcn_s_sleep(1); \
;     if ((++_sp & 255u) == 0u) { if (xb_ld(&(bar)[XB_TMO])) break; if (_sp > XB_SPIN_CAP) { atomicAdd(&(bar)[XB_TMO], 1u); break; } } } } while (0)
; __device__ __forceinline__ void xcd_barrier(const XcdBarrier& b) {
;     ...
;         const unsigned old = xb_add(&bar[XB_XSUB(b.x)], 1u);
;         const unsigned gen = old / nloc;
;         if (old + 1u == (gen + 1u) * nloc) {
;             __builtin_amdgcn_fence(__ATOMIC_RELEASE, "agent");
;             asm volatile("s_waitcnt vmcnt(0)" ::: "memory");
;             const unsigned og = xb_add(&bar[XB_TOP], 1u);
;             const unsigned tg = og / nx;
;             if (og + 1u == (tg + 1u) * nx) xb_add(&bar[XB_TOPGEN], 1u);
;             else XB_SPIN(xb_ld(&bar[XB_TOPGEN]) == tg, bar);
.LBB0_682:
	s_andn2_saveexec_b64 s[0:1], s[0:1]
	s_cbranch_execz .LBB0_698
	v_mov_b32_e32 v1, s34
	v_add_co_u32_e32 v2, vcc, 0x3000, v1
	v_mov_b32_e32 v1, s35
	buffer_wbl2 sc1
	s_waitcnt vmcnt(0)
	v_addc_co_u32_e32 v3, vcc, 0, v1, vcc
	v_mov_b32_e32 v1, 1
	flat_atomic_add v1, v[2:3], v1 offset:1024 sc0
	buffer_inv sc1
	v_cvt_f32_u32_e32 v2, v0
	v_sub_u32_e32 v3, 0, v0
	s_mov_b64 s[4:5], -1
	v_rcp_iflag_f32_e32 v2, v2
	s_nop 0
	v_mul_f32_e32 v2, 0x4f7ffffe, v2
	v_cvt_u32_f32_e32 v2, v2
	v_mul_lo_u32 v3, v3, v2
	v_mul_hi_u32 v3, v2, v3
	v_add_u32_e32 v2, v2, v3
	s_waitcnt vmcnt(0) lgkmcnt(0)
	v_mul_hi_u32 v2, v1, v2
	v_mul_lo_u32 v3, v2, v0
	v_sub_u32_e32 v3, v1, v3
	v_cmp_ge_u32_e32 vcc, v3, v0
	v_add_u32_e32 v4, 1, v2
	s_nop 0
	v_cndmask_b32_e32 v2, v2, v4, vcc
	v_sub_u32_e32 v4, v3, v0
	v_cndmask_b32_e32 v3, v3, v4, vcc
	v_cmp_ge_u32_e32 vcc, v3, v0
	v_add_u32_e32 v3, 1, v2
	s_nop 0
	v_cndmask_b32_e32 v2, v2, v3, vcc
	v_add_u32_e32 v3, 1, v1
	v_mad_u64_u32 v[0:1], s[0:1], v0, v2, v[0:1]
	s_add_u32 s0, s34, 0x3500
	s_addc_u32 s1, s35, 0
	v_cmp_ne_u32_e32 vcc, v3, v0
	v_mov_b64_e32 v[0:1], s[0:1]
	s_and_saveexec_b64 s[2:3], vcc
	s_cbranch_execz .LBB0_695
	v_mov_b64_e32 v[0:1], s[0:1]
	flat_load_dword v0, v[0:1] sc1
	s_mov_b64 s[8:9], 0
	s_waitcnt vmcnt(0) lgkmcnt(0)
	v_cmp_eq_u32_e32 vcc, v0, v2
	s_and_saveexec_b64 s[6:7], vcc
	s_cbranch_execz .LBB0_694
	s_add_u32 s4, s34, 0x200
	s_addc_u32 s5, s35, 0
	s_mov_b32 s21, 1
	s_branch .LBB0_687

; __device__ __forceinline__ unsigned xb_ld(unsigned* p)              { return __hip_atomic_load(p, __ATOMIC_RELAXED, __HIP_MEMORY_SCOPE_AGENT); }
; __device__ __forceinline__ unsigned xb_add(unsigned* p, unsigned v) { return __hip_atomic_fetch_add(p, v, __ATOMIC_RELAXED, __HIP_MEMORY_SCOPE_AGENT); }
; #define XB_SPIN(cond, bar) do { unsigned _sp = 0; while (cond) { __builtin_amdgcn_s_sleep(1); \
;     if ((++_sp & 255u) == 0u) { if (xb_ld(&(bar)[XB_TMO])) break; if (_sp > XB_SPIN_CAP) { atomicAdd(&(bar)[XB_TMO], 1u); break; } } } } while (0)
; __device__ __forceinline__ void xcd_barrier(const XcdBarrier& b) {
;     ...
;         const unsigned old = xb_add(&bar[XB_XSUB(b.x)], 1u);
;         const unsigned gen = old / nloc;
;         if (old + 1u == (gen + 1u) * nloc) {
;             __builtin_amdgcn_fence(__ATOMIC_RELEASE, "agent");
;             asm volatile("s_waitcnt vmcnt(0)" ::: "memory");
;             const unsigned og = xb_add(&bar[XB_TOP], 1u);
;             const unsigned tg = og / nx;
;             if (og + 1u == (tg + 1u) * nx) xb_add(&bar[XB_TOPGEN], 1u);
;             else XB_SPIN(xb_ld(&bar[XB_TOPGEN]) == tg, bar);
.LBB0_841:
	s_andn2_saveexec_b64 s[0:1], s[0:1]
	s_cbranch_execz .LBB0_857
	v_mov_b32_e32 v1, s36
	v_add_co_u32_e32 v2, vcc, 0x3000, v1
	v_mov_b32_e32 v1, s37
	buffer_wbl2 sc1
	s_waitcnt vmcnt(0)
	v_addc_co_u32_e32 v3, vcc, 0, v1, vcc
	v_mov_b32_e32 v1, 1
	flat_atomic_add v1, v[2:3], v1 offset:1024 sc0
	buffer_inv sc1
	v_cvt_f32_u32_e32 v2, v0
	v_sub_u32_e32 v3, 0, v0
	s_mov_b64 s[6:7], -1
	v_rcp_iflag_f32_e32 v2, v2
	s_nop 0
	v_mul_f32_e32 v2, 0x4f7ffffe, v2
	v_cvt_u32_f32_e32 v2, v2
	v_mul_lo_u32 v3, v3, v2
	v_mul_hi_u32 v3, v2, v3
	v_add_u32_e32 v2, v2, v3
	s_waitcnt vmcnt(0) lgkmcnt(0)
	v_mul_hi_u32 v2, v1, v2
	v_mul_lo_u32 v3, v2, v0
	v_sub_u32_e32 v3, v1, v3
	v_cmp_ge_u32_e32 vcc, v3, v0
	v_add_u32_e32 v4, 1, v2
	s_nop 0
	v_cndmask_b32_e32 v2, v2, v4, vcc
	v_sub_u32_e32 v4, v3, v0
	v_cndmask_b32_e32 v3, v3, v4, vcc
	v_cmp_ge_u32_e32 vcc, v3, v0
	v_add_u32_e32 v3, 1, v2
	s_nop 0
	v_cndmask_b32_e32 v2, v2, v3, vcc
	v_add_u32_e32 v3, 1, v1
	v_mad_u64_u32 v[0:1], s[0:1], v0, v2, v[0:1]
	s_add_u32 s0, s36, 0x3500
	s_addc_u32 s1, s37, 0
	v_cmp_ne_u32_e32 vcc, v3, v0
	v_mov_b64_e32 v[0:1], s[0:1]
	s_and_saveexec_b64 s[2:3], vcc
	s_cbranch_execz .LBB0_854
	v_mov_b64_e32 v[0:1], s[0:1]
	flat_load_dword v0, v[0:1] sc1
	s_mov_b64 s[10:11], 0
	s_waitcnt vmcnt(0) lgkmcnt(0)
	v_cmp_eq_u32_e32 vcc, v0, v2
	s_and_saveexec_b64 s[8:9], vcc
	s_cbranch_execz .LBB0_853
	s_add_u32 s6, s36, 0x200
	s_addc_u32 s7, s37, 0
	s_mov_b32 s23, 1
	s_branch .LBB0_846

; __device__ __forceinline__ unsigned xb_ld(unsigned* p)              { return __hip_atomic_load(p, __ATOMIC_RELAXED, __HIP_MEMORY_SCOPE_AGENT); }
; __device__ __forceinline__ unsigned xb_add(unsigned* p, unsigned v) { return __hip_atomic_fetch_add(p, v, __ATOMIC_RELAXED, __HIP_MEMORY_SCOPE_AGENT); }
; #define XB_SPIN(cond, bar) do { unsigned _sp = 0; while (cond) { __builtin_amdgcn_s_sleep(1); \
;     if ((++_sp & 255u) == 0u) { if (xb_ld(&(bar)[XB_TMO])) break; if (_sp > XB_SPIN_CAP) { atomicAdd(&(bar)[XB_TMO], 1u); break; } } } } while (0)
; __device__ __forceinline__ void xcd_barrier(const XcdBarrier& b) {
;     ...
;         const unsigned old = xb_add(&bar[XB_XSUB(b.x)], 1u);
;         const unsigned gen = old / nloc;
;         if (old + 1u == (gen + 1u) * nloc) {
;             __builtin_amdgcn_fence(__ATOMIC_RELEASE, "agent");
;             asm volatile("s_waitcnt vmcnt(0)" ::: "memory");
;             const unsigned og = xb_add(&bar[XB_TOP], 1u);
;             const unsigned tg = og / nx;
;             if (og + 1u == (tg + 1u) * nx) xb_add(&bar[XB_TOPGEN], 1u);
;             else XB_SPIN(xb_ld(&bar[XB_TOPGEN]) == tg, bar);
.LBB0_1365:
	v_mov_b32_e32 v1, s34
	v_add_co_u32_e32 v2, vcc, 0x3000, v1
	v_mov_b32_e32 v1, s35
	buffer_wbl2 sc1
	s_waitcnt vmcnt(0)
	v_addc_co_u32_e32 v3, vcc, 0, v1, vcc
	v_mov_b32_e32 v1, 1
	flat_atomic_add v1, v[2:3], v1 offset:1024 sc0
	buffer_inv sc1
	v_cvt_f32_u32_e32 v2, v0
	v_sub_u32_e32 v3, 0, v0
	s_mov_b64 s[4:5], -1
	v_rcp_iflag_f32_e32 v2, v2
	s_nop 0
	v_mul_f32_e32 v2, 0x4f7ffffe, v2
	v_cvt_u32_f32_e32 v2, v2
	v_mul_lo_u32 v3, v3, v2
	v_mul_hi_u32 v3, v2, v3
	v_add_u32_e32 v2, v2, v3
	s_waitcnt vmcnt(0) lgkmcnt(0)
	v_mul_hi_u32 v2, v1, v2
	v_mul_lo_u32 v3, v2, v0
	v_sub_u32_e32 v3, v1, v3
	v_cmp_ge_u32_e32 vcc, v3, v0
	v_add_u32_e32 v4, 1, v2
	s_nop 0
	v_cndmask_b32_e32 v2, v2, v4, vcc
	v_sub_u32_e32 v4, v3, v0
	v_cndmask_b32_e32 v3, v3, v4, vcc
	v_cmp_ge_u32_e32 vcc, v3, v0
	v_add_u32_e32 v3, 1, v2
	s_nop 0
	v_cndmask_b32_e32 v2, v2, v3, vcc
	v_add_u32_e32 v3, 1, v1
	v_mad_u64_u32 v[0:1], s[0:1], v0, v2, v[0:1]
	s_add_u32 s0, s34, 0x3500
	s_addc_u32 s1, s35, 0
	v_cmp_ne_u32_e32 vcc, v3, v0
	v_mov_b64_e32 v[0:1], s[0:1]
	s_and_saveexec_b64 s[2:3], vcc
	s_cbranch_execz .LBB0_1377
	v_mov_b64_e32 v[0:1], s[0:1]
	flat_load_dword v0, v[0:1] sc1
	s_mov_b64 s[8:9], 0
	s_waitcnt vmcnt(0) lgkmcnt(0)
	v_cmp_eq_u32_e32 vcc, v0, v2
	s_and_saveexec_b64 s[6:7], vcc
	s_cbranch_execz .LBB0_1376
	s_add_u32 s4, s34, 0x200
	s_addc_u32 s5, s35, 0
	s_mov_b32 s21, 1
	s_branch .LBB0_1369
